# attention KV-tile loop .LBB0_616: 4 staging global loads issued together, then the 4 LDS writes (was load/wait/write x4)
# baseline (speedup 1.0000x reference)
; DI int otid() { int t = threadIdx.x; asm volatile("" : "+v"(t)); return t; }
; DI f32x16 mfma32(bf16x8 a, bf16x8 b, f32x16 c) { return __builtin_amdgcn_mfma_f32_32x32x16_bf16(a, b, c, 0, 0, 0); }
; DI f32x16 zero16() { f32x16 z; for (int i = 0; i < 16; ++i) z[i] = 0.f; return z; }
; DI int crow(int i, int h) { return (i & 3) + 8 * (i >> 2) + 4 * h; }
; DI void stage64(uchar* dst, const u16* src, size_t row_stride) {
;   const int tid = otid();
; #pragma unroll
;   for (int i = 0; i < 2; ++i) {
;     int c = tid + 256 * i, row = c >> 3, kc = c & 7;
;     uint4 v = *(const uint4*)(src + (size_t)row * row_stride + kc * 8);
;     *(uint4*)(dst + row * 144 + kc * 16) = v;
;   }
; }
; DI void qk_tile(f32x16 st[2], const bf16x8* qf, int s0, int ns, const uchar* Ks, int r31, int h) {
; #pragma unroll
;   for (int kt = 0; kt < 2; ++kt) {
;     st[kt] = zero16();
; #pragma unroll
;     for (int s = 0; s < ns; ++s) {
;       bf16x8 kf = *(const bf16x8*)(Ks + (32 * kt + r31) * 144 + (2 * (s0 + s) + h) * 16);
;       st[kt] = mfma32(kf, qf[s0 + s], st[kt]);
;     }
;   }
; }
; DI void nsa_item(const Params& P0_, int b, int item, uchar* smem) {
;     ...
;     for (int t = 0; t < ntl; ++t) {
;       const int n0 = t * 64;
;       __syncthreads();
;       stage64(Ks, KC + ((size_t)b * 256 + n0) * 64, 64);
;       stage64(Vs, VC + ((size_t)b * 256 + n0) * 64, 64);
;       __syncthreads();
;       f32x16 st[2]; bf16x8 pf[4];
;       qk_tile(st, qf, 0, 4, Ks, r31, h);
; #pragma unroll
;       for (int kt = 0; kt < 2; ++kt)
; #pragma unroll
;         for (int i = 0; i < 16; ++i) {
;           int n = n0 + 32 * kt + crow(i, h);
;           st[kt][i] = (16 * n + 31 <= qpos) ? st[kt][i] * c2 : -INFINITY;
;         }
.LBB0_616:
	v_mov_b32_e32 v71, v166
	s_barrier
	s_nop 0
	v_ashrrev_i32_e32 v72, 3, v71
	v_lshlrev_b32_e32 v66, 4, v71
	v_ashrrev_i32_e32 v73, 31, v72
	v_and_b32_e32 v70, 0x70, v66
	v_add_u32_e32 v82, 0x100, v71
	v_ashrrev_i32_e32 v84, 3, v82
	v_ashrrev_i32_e32 v85, 31, v84
	v_lshlrev_b64 v[92:93], 7, v[72:73]
	v_lshlrev_b64 v[66:67], 7, v[84:85]
	v_or_b32_e32 v92, v92, v70
	v_or_b32_e32 v66, v66, v70
	v_lshl_add_u64 v[92:93], s[6:7], 0, v[92:93]
	v_lshl_add_u64 v[66:67], s[6:7], 0, v[66:67]
	v_add_co_u32_e32 v74, vcc, s17, v92
	s_nop 1
	v_addc_co_u32_e32 v75, vcc, -1, v93, vcc
	global_load_dwordx4 v[78:81], v[74:75], off
	v_add_co_u32_e32 v82, vcc, s17, v66
	s_nop 1
	v_addc_co_u32_e32 v83, vcc, -1, v67, vcc
	global_load_dwordx4 v[88:91], v[82:83], off
	global_load_dwordx4 v[94:97], v[92:93], off
	global_load_dwordx4 v[66:69], v[66:67], off
	v_mad_u64_u32 v[76:77], s[0:1], v72, s16, v[70:71]
	v_mad_u64_u32 v[86:87], s[0:1], v84, s16, v[70:71]
	s_waitcnt vmcnt(3)
	ds_write_b128 v76, v[78:81]
	s_waitcnt vmcnt(2)
	ds_write_b128 v86, v[88:91]
	s_waitcnt vmcnt(1)
	ds_write_b128 v76, v[94:97] offset:9216
	s_waitcnt vmcnt(0)
	ds_write_b128 v86, v[66:69] offset:9216
	s_waitcnt lgkmcnt(0)
	s_barrier
	ds_read_b128 v[66:69], v108
	ds_read_b128 v[70:73], v108 offset:32
	s_waitcnt lgkmcnt(1)
	v_mfma_f32_32x32x16_bf16 v[82:97], v[66:69], v[134:137], 0
	ds_read_b128 v[66:69], v108 offset:64
	ds_read_b128 v[110:113], v108 offset:4640
	s_waitcnt lgkmcnt(2)
	v_mfma_f32_32x32x16_bf16 v[82:97], v[70:73], v[138:141], v[82:97]
	s_waitcnt lgkmcnt(1)
	v_mfma_f32_32x32x16_bf16 v[82:97], v[66:69], v[142:145], v[82:97]
	ds_read_b128 v[66:69], v108 offset:96
	s_waitcnt lgkmcnt(0)
	v_mfma_f32_32x32x16_bf16 v[82:97], v[66:69], v[146:149], v[82:97]
	ds_read_b128 v[66:69], v108 offset:4608
	s_waitcnt lgkmcnt(0)
	v_mfma_f32_32x32x16_bf16 v[66:81], v[66:69], v[134:137], 0
	s_nop 8
	v_mul_f32_e32 v82, 0x3e38aa3b, v82
	v_mul_f32_e32 v83, 0x3e38aa3b, v83
	v_mul_f32_e32 v84, 0x3e38aa3b, v84
	v_mul_f32_e32 v85, 0x3e38aa3b, v85
	v_mul_f32_e32 v86, 0x3e38aa3b, v86
	v_mul_f32_e32 v87, 0x3e38aa3b, v87
	v_mul_f32_e32 v88, 0x3e38aa3b, v88
	v_mfma_f32_32x32x16_bf16 v[66:81], v[110:113], v[138:141], v[66:81]
	ds_read_b128 v[110:113], v108 offset:4672
	v_mul_f32_e32 v89, 0x3e38aa3b, v89
	v_mul_f32_e32 v90, 0x3e38aa3b, v90
	v_mul_f32_e32 v91, 0x3e38aa3b, v91
	v_mul_f32_e32 v92, 0x3e38aa3b, v92
	v_mul_f32_e32 v93, 0x3e38aa3b, v93
	v_mul_f32_e32 v94, 0x3e38aa3b, v94
	s_waitcnt lgkmcnt(0)
	v_mfma_f32_32x32x16_bf16 v[66:81], v[110:113], v[142:145], v[66:81]
	ds_read_b128 v[110:113], v108 offset:4704
	v_mul_f32_e32 v95, 0x3e38aa3b, v95
	v_mul_f32_e32 v96, 0x3e38aa3b, v96
	v_mul_f32_e32 v97, 0x3e38aa3b, v97
	s_waitcnt lgkmcnt(0)
	v_mfma_f32_32x32x16_bf16 v[66:81], v[110:113], v[146:149], v[66:81]
	v_add_u32_e32 v111, 0xfffffc50, v107
	v_cmp_le_i32_e32 vcc, v111, v100
	v_add_u32_e32 v111, 0xfffffc60, v107
	v_add_u32_e32 v110, s9, v127
	v_cndmask_b32_e32 v82, v233, v82, vcc
	v_cmp_le_i32_e32 vcc, v111, v100
	v_add_u32_e32 v111, 0xfffffc70, v107
	s_nop 4
	v_mul_f32_e32 v66, 0x3e38aa3b, v66
	v_cndmask_b32_e32 v83, v233, v83, vcc
	v_cmp_le_i32_e32 vcc, v111, v100
	v_add_u32_e32 v111, 0xfffffc80, v107
	v_mul_f32_e32 v67, 0x3e38aa3b, v67
	v_cndmask_b32_e32 v84, v233, v84, vcc
	v_cmp_le_i32_e32 vcc, v111, v100
	v_add_u32_e32 v111, 0xfffffcd0, v107
	v_mul_f32_e32 v68, 0x3e38aa3b, v68
	v_cndmask_b32_e32 v85, v233, v85, vcc
	v_cmp_le_i32_e32 vcc, v111, v100
	v_add_u32_e32 v111, 0xfffffce0, v107
	v_mul_f32_e32 v69, 0x3e38aa3b, v69
	v_cndmask_b32_e32 v86, v233, v86, vcc
	v_cmp_le_i32_e32 vcc, v111, v100
	v_add_u32_e32 v111, 0xfffffcf0, v107
	v_mul_f32_e32 v70, 0x3e38aa3b, v70
	v_cndmask_b32_e32 v87, v233, v87, vcc
	v_cmp_le_i32_e32 vcc, v111, v100
	v_add_u32_e32 v111, 0xfffffd00, v107
	v_mul_f32_e32 v71, 0x3e38aa3b, v71
	v_cndmask_b32_e32 v88, v233, v88, vcc
	v_cmp_le_i32_e32 vcc, v111, v100
	v_add_u32_e32 v111, 0xfffffd50, v107
	v_mul_f32_e32 v72, 0x3e38aa3b, v72
	v_cndmask_b32_e32 v89, v233, v89, vcc
	v_cmp_le_i32_e32 vcc, v111, v100
	v_add_u32_e32 v111, 0xfffffd60, v107
	v_mul_f32_e32 v73, 0x3e38aa3b, v73
	v_cndmask_b32_e32 v90, v233, v90, vcc
	v_cmp_le_i32_e32 vcc, v111, v100
	v_add_u32_e32 v111, 0xfffffd70, v107
	v_mul_f32_e32 v74, 0x3e38aa3b, v74
	v_cndmask_b32_e32 v91, v233, v91, vcc
	v_cmp_le_i32_e32 vcc, v111, v100
	v_add_u32_e32 v111, 0xfffffd80, v107
	v_mul_f32_e32 v75, 0x3e38aa3b, v75
	v_cndmask_b32_e32 v92, v233, v92, vcc
	v_cmp_le_i32_e32 vcc, v111, v100
	v_add_u32_e32 v111, 0xfffffdd0, v107
	v_cmp_gt_u32_e64 s[0:1], v110, v104
	v_cndmask_b32_e32 v93, v233, v93, vcc
	v_cmp_le_i32_e32 vcc, v111, v100
	v_add_u32_e32 v111, 0xfffffde0, v107
	v_add_u32_e32 v156, 1, v110
	v_cndmask_b32_e32 v94, v233, v94, vcc
	v_cmp_le_i32_e32 vcc, v111, v100
	v_add_u32_e32 v111, 0xfffffdf0, v107
	v_add_u32_e32 v158, 2, v110
	v_cndmask_b32_e32 v95, v233, v95, vcc
	v_cmp_le_i32_e32 vcc, v111, v100
	v_add_u32_e32 v111, 0xfffffe00, v107
	v_max_f32_e32 v115, v94, v95
	v_cndmask_b32_e32 v96, v233, v96, vcc
	v_cmp_le_i32_e32 vcc, v111, v100
	v_add_u32_e32 v111, 0xfffffe50, v107
	v_add_u32_e32 v159, 3, v110
	v_cndmask_b32_e32 v97, v233, v97, vcc
	v_cmp_le_i32_e32 vcc, v111, v100
	v_add_u32_e32 v111, 0xfffffe60, v107
	v_add_u32_e32 v161, 8, v110
	v_cndmask_b32_e32 v66, v233, v66, vcc
	v_cmp_le_i32_e32 vcc, v111, v100
	v_add_u32_e32 v111, 0xfffffe70, v107
	v_add_u32_e32 v162, 9, v110
	v_cndmask_b32_e32 v67, v233, v67, vcc
	v_cmp_le_i32_e32 vcc, v111, v100
	v_add_u32_e32 v111, 0xfffffe80, v107
	v_add_u32_e32 v164, 10, v110
	v_cndmask_b32_e32 v68, v233, v68, vcc
	v_cmp_le_i32_e32 vcc, v111, v100
	v_add_u32_e32 v111, 0xfffffed0, v107
; DI f32x16 mfma32(bf16x8 a, bf16x8 b, f32x16 c) { return __builtin_amdgcn_mfma_f32_32x32x16_bf16(a, b, c, 0, 0, 0); }
; DI void pv_tile(f32x16 O[2], const bf16x8 pf[4], const uchar* Vs, int lane) {
;   const int h = lane >> 5, blk = (lane >> 4) & 1, q4 = (lane & 15) >> 2, p = lane & 3;
; #pragma unroll
;   for (int sp = 0; sp < 4; ++sp) {
; #pragma unroll
;     for (int dt = 0; dt < 2; ++dt) {
;       const uchar* a = Vs + (16 * sp + 4 * h + q4) * 144 + 64 * dt + 32 * blk + 8 * p;
;       s16x4 lo = tr_read(a), hi = tr_read(a + 8 * 144);
;       bf16x8 vf = __builtin_shufflevector(lo, hi, 0, 1, 2, 3, 4, 5, 6, 7);
;       O[dt] = mfma32(vf, pf[sp], O[dt]);
;     }
;   }
; }
; template <int NO, bool COND>
; DI void sm_rescale(float& m, float mx, float& lsum, f32x16* O) {
;   if (!COND || __builtin_amdgcn_ballot_w64(mx > m) != 0ull) {
;     const float corr = __builtin_amdgcn_exp2f(m - mx);
;     lsum *= corr;
; #pragma unroll
;     for (int o = 0; o < NO; ++o)
; #pragma unroll
;       for (int i = 0; i < 16; ++i) O[o][i] *= corr;
;   }
;   m = mx;
; }
; DI float max16(const f32x16& x) {
;   float a = fmaxf(fmaxf(x[0], x[1]), x[2]), b = fmaxf(fmaxf(x[3], x[4]), x[5]), c = fmaxf(fmaxf(x[6], x[7]), x[8]);
;   float d = fmaxf(fmaxf(x[9], x[10]), x[11]), e = fmaxf(fmaxf(x[12], x[13]), x[14]);
;   return fmaxf(fmaxf(fmaxf(a, b), fmaxf(c, d)), fmaxf(e, x[15]));
; }
; template <int NO, bool COND = true>
; DI void softmax_step(f32x16 st[2], float& m, float& lsum, f32x16* O, bf16x8 pf[4]) {
;   float mx = fmaxf(m, fmaxf(max16(st[0]), max16(st[1])));
;   mx = fmaxf(mx, __shfl_xor(mx, 32, 64));
;   sm_rescale<NO, COND>(m, mx, lsum, O);
; #pragma unroll
;   for (int kt = 0; kt < 2; ++kt)
; #pragma unroll
;     for (int i = 0; i < 16; ++i) { float p = __builtin_amdgcn_exp2f(st[kt][i] - mx); lsum += p; st[kt][i] = p; }
; #pragma unroll
;   for (int kt = 0; kt < 2; ++kt) { pf[2 * kt] = pack8(st[kt], 0); pf[2 * kt + 1] = pack8(st[kt], 1); }
; }
	v_add_u32_e32 v165, 11, v110
	v_cndmask_b32_e32 v69, v233, v69, vcc
	v_cmp_le_i32_e32 vcc, v111, v100
	v_add_u32_e32 v111, 0xfffffee0, v107
	s_add_i32 s9, s9, 64
	v_cndmask_b32_e32 v70, v233, v70, vcc
	v_cmp_le_i32_e32 vcc, v111, v100
	v_add_u32_e32 v111, 0xfffffef0, v107
	s_nop 0
	v_cndmask_b32_e32 v71, v233, v71, vcc
	v_cmp_le_i32_e32 vcc, v111, v100
	v_add_u32_e32 v111, 0xffffff00, v107
	s_nop 0
	v_cndmask_b32_e32 v72, v233, v72, vcc
	v_cmp_le_i32_e32 vcc, v111, v100
	v_add_u32_e32 v111, 0xffffff50, v107
	s_nop 0
	v_cndmask_b32_e32 v73, v233, v73, vcc
	v_cmp_le_i32_e32 vcc, v111, v100
	s_nop 1
	v_cndmask_b32_e32 v111, v233, v74, vcc
	v_add_u32_e32 v74, 0xffffff60, v107
	v_cmp_le_i32_e32 vcc, v74, v100
	v_add_u32_e32 v74, 0xffffff70, v107
	s_nop 0
	v_cndmask_b32_e32 v112, v233, v75, vcc
	v_mul_f32_e32 v75, 0x3e38aa3b, v76
	v_cmp_le_i32_e32 vcc, v74, v100
	v_add_u32_e32 v74, 0xffffff80, v107
	v_max_f32_e32 v76, v88, v89
	v_cndmask_b32_e32 v113, v233, v75, vcc
	v_mul_f32_e32 v75, 0x3e38aa3b, v77
	v_cmp_le_i32_e32 vcc, v74, v100
	v_subrev_u32_e32 v74, 48, v107
	v_max3_f32 v77, v91, v92, v93
	v_cndmask_b32_e32 v114, v233, v75, vcc
	v_mul_f32_e32 v75, 0x3e38aa3b, v78
	v_cmp_le_i32_e32 vcc, v74, v100
	v_subrev_u32_e32 v74, 32, v107
	s_nop 0
	v_cndmask_b32_e32 v78, v233, v75, vcc
	v_mul_f32_e32 v75, 0x3e38aa3b, v79
	v_cmp_le_i32_e32 vcc, v74, v100
	v_add_u32_e32 v74, -16, v107
	s_nop 0
	v_cndmask_b32_e32 v79, v233, v75, vcc
	v_mul_f32_e32 v75, 0x3e38aa3b, v80
	v_cmp_le_i32_e32 vcc, v74, v100
	v_mul_f32_e32 v74, 0x3e38aa3b, v81
	v_max_f32_e32 v116, v78, v79
	v_cndmask_b32_e32 v80, v233, v75, vcc
	v_cmp_le_i32_e32 vcc, v107, v100
	v_max3_f32 v75, v85, v86, v87
	v_add_u32_e32 v107, 0x400, v107
	v_cndmask_b32_e32 v81, v233, v74, vcc
	v_max_f32_e32 v74, v82, v83
	v_max3_f32 v74, v74, v84, v75
	v_max3_f32 v75, v76, v90, v77
	v_max3_f32 v76, v115, v96, v97
	v_max3_f32 v74, v74, v75, v76
	v_max_f32_e32 v75, v66, v67
	v_max3_f32 v76, v69, v70, v71
	v_max_f32_e32 v77, v72, v73
	v_max3_f32 v115, v112, v113, v114
	v_max3_f32 v75, v75, v68, v76
	v_max3_f32 v76, v77, v111, v115
	v_max3_f32 v77, v116, v80, v81
	v_max3_f32 v75, v75, v76, v77
	v_mbcnt_hi_u32_b32 v76, -1, v230
	v_max3_f32 v77, v0, v74, v75
	v_and_b32_e32 v75, 64, v76
	v_xor_b32_e32 v74, 32, v76
	v_add_u32_e32 v75, 64, v75
	v_cmp_lt_i32_e32 vcc, v74, v75
	s_nop 1
	v_cndmask_b32_e32 v115, v76, v74, vcc
	v_lshlrev_b32_e32 v115, 2, v115
	ds_bpermute_b32 v115, v115, v77
	v_cmp_lt_i32_e32 vcc, v110, v103
	s_or_b64 s[0:1], vcc, s[0:1]
	v_cmp_lt_i32_e32 vcc, v156, v103
	s_waitcnt lgkmcnt(0)
	v_max_f32_e32 v115, v115, v115
	v_max_f32_e32 v77, v77, v115
	v_sub_f32_e32 v66, v66, v77
	v_exp_f32_e32 v123, v66
	v_sub_f32_e32 v66, v67, v77
	v_exp_f32_e32 v124, v66
	v_sub_f32_e32 v66, v68, v77
	v_sub_f32_e32 v82, v82, v77
	v_exp_f32_e32 v125, v66
	v_sub_f32_e32 v66, v69, v77
	v_exp_f32_e32 v115, v82
	v_sub_f32_e32 v82, v83, v77
	v_exp_f32_e32 v130, v66
	v_sub_f32_e32 v66, v70, v77
	v_exp_f32_e32 v116, v82
	v_sub_f32_e32 v82, v84, v77
	v_exp_f32_e32 v131, v66
	v_sub_f32_e32 v66, v71, v77
	v_exp_f32_e32 v117, v82
	v_sub_f32_e32 v82, v85, v77
	v_exp_f32_e32 v132, v66
	v_sub_f32_e32 v66, v72, v77
	v_exp_f32_e32 v118, v82
	v_sub_f32_e32 v82, v86, v77
	v_exp_f32_e32 v150, v66
	v_sub_f32_e32 v66, v73, v77
	v_exp_f32_e32 v119, v82
	v_sub_f32_e32 v82, v87, v77
	v_exp_f32_e32 v151, v66
	v_sub_f32_e32 v66, v111, v77
	v_exp_f32_e32 v120, v82
	v_sub_f32_e32 v82, v88, v77
	v_exp_f32_e32 v111, v66
	v_sub_f32_e32 v66, v112, v77
	v_sub_f32_e32 v0, v0, v77
	v_exp_f32_e32 v121, v82
	v_sub_f32_e32 v82, v89, v77
	v_exp_f32_e32 v112, v66
	v_sub_f32_e32 v66, v113, v77
	v_exp_f32_e32 v0, v0
	v_exp_f32_e32 v122, v82
	v_exp_f32_e32 v113, v66
	v_sub_f32_e32 v66, v114, v77
	ds_read_b64_tr_b16 v[86:87], v109 offset:9216
	ds_read_b64_tr_b16 v[88:89], v109 offset:10368
	v_exp_f32_e32 v114, v66
	v_sub_f32_e32 v66, v78, v77
	v_sub_f32_e32 v82, v90, v77
	v_exp_f32_e32 v152, v66
	v_sub_f32_e32 v66, v79, v77
	v_exp_f32_e32 v90, v82
	v_sub_f32_e32 v82, v91, v77
	v_exp_f32_e32 v153, v66
	v_sub_f32_e32 v66, v80, v77
	v_pk_mul_f32 v[32:33], v[32:33], v[0:1] op_sel_hi:[1,0]
	v_pk_mul_f32 v[30:31], v[30:31], v[0:1] op_sel_hi:[1,0]
	v_pk_mul_f32 v[28:29], v[28:29], v[0:1] op_sel_hi:[1,0]
	v_pk_mul_f32 v[26:27], v[26:27], v[0:1] op_sel_hi:[1,0]
	v_pk_mul_f32 v[24:25], v[24:25], v[0:1] op_sel_hi:[1,0]
	v_pk_mul_f32 v[22:23], v[22:23], v[0:1] op_sel_hi:[1,0]
	v_pk_mul_f32 v[20:21], v[20:21], v[0:1] op_sel_hi:[1,0]
	v_pk_mul_f32 v[18:19], v[18:19], v[0:1] op_sel_hi:[1,0]
	v_exp_f32_e32 v91, v82
	v_sub_f32_e32 v82, v92, v77
	v_exp_f32_e32 v154, v66
	v_sub_f32_e32 v66, v81, v77
	v_cvt_pk_bf16_f32 v78, v115, v116
	v_cvt_pk_bf16_f32 v79, v117, v118
	v_cvt_pk_bf16_f32 v80, v119, v120
	v_cvt_pk_bf16_f32 v81, v121, v122
	v_exp_f32_e32 v92, v82
	v_sub_f32_e32 v82, v93, v77
	s_waitcnt lgkmcnt(0)
	v_mfma_f32_32x32x16_bf16 v[18:33], v[86:89], v[78:81], v[18:33]
	ds_read_b64_tr_b16 v[86:87], v109 offset:9280
	ds_read_b64_tr_b16 v[88:89], v109 offset:10432
	v_exp_f32_e32 v93, v82
	v_sub_f32_e32 v82, v94, v77
	v_exp_f32_e32 v94, v82
	v_sub_f32_e32 v82, v95, v77
	v_exp_f32_e32 v95, v82
	v_sub_f32_e32 v82, v96, v77
	v_pk_mul_f32 v[16:17], v[16:17], v[0:1] op_sel_hi:[1,0]
	v_pk_mul_f32 v[14:15], v[14:15], v[0:1] op_sel_hi:[1,0]
	v_pk_mul_f32 v[12:13], v[12:13], v[0:1] op_sel_hi:[1,0]
	v_pk_mul_f32 v[10:11], v[10:11], v[0:1] op_sel_hi:[1,0]
	v_pk_mul_f32 v[8:9], v[8:9], v[0:1] op_sel_hi:[1,0]
	v_pk_mul_f32 v[6:7], v[6:7], v[0:1] op_sel_hi:[1,0]
	v_pk_mul_f32 v[4:5], v[4:5], v[0:1] op_sel_hi:[1,0]
	v_pk_mul_f32 v[2:3], v[2:3], v[0:1] op_sel_hi:[1,0]
	v_exp_f32_e32 v96, v82
	v_sub_f32_e32 v82, v97, v77
	v_exp_f32_e32 v97, v82
	s_waitcnt lgkmcnt(0)
; DI f32x16 mfma32(bf16x8 a, bf16x8 b, f32x16 c) { return __builtin_amdgcn_mfma_f32_32x32x16_bf16(a, b, c, 0, 0, 0); }
; DI void pv_tile(f32x16 O[2], const bf16x8 pf[4], const uchar* Vs, int lane) {
;   const int h = lane >> 5, blk = (lane >> 4) & 1, q4 = (lane & 15) >> 2, p = lane & 3;
; #pragma unroll
;   for (int sp = 0; sp < 4; ++sp) {
; #pragma unroll
;     for (int dt = 0; dt < 2; ++dt) {
;       const uchar* a = Vs + (16 * sp + 4 * h + q4) * 144 + 64 * dt + 32 * blk + 8 * p;
;       s16x4 lo = tr_read(a), hi = tr_read(a + 8 * 144);
;       bf16x8 vf = __builtin_shufflevector(lo, hi, 0, 1, 2, 3, 4, 5, 6, 7);
;       O[dt] = mfma32(vf, pf[sp], O[dt]);
;     }
;   }
; }
; DI void nsa_item(const Params& P0_, int b, int item, uchar* smem) {
;     ...
;       for (int sp = 0; sp < 4; ++sp) {
; #pragma unroll
;         for (int u = 0; u < 2; ++u) {
;           const int j = 32 * u + r31;
;           bf16x8 of;
; #pragma unroll
;           for (int jj = 0; jj < 8; ++jj) {
;             int n = n0 + 16 * sp + 8 * (jj >> 2) + 4 * h + (jj & 3);
;             of[jj] = (n >= 4 * j - 1 && n <= 4 * j + 3) ? (short)0x3F80 : (short)0;
;           }
;           O[2 + u] = mfma32(of, pf[sp], O[2 + u]);
;         }
;       }
	v_mfma_f32_32x32x16_bf16 v[2:17], v[86:89], v[78:81], v[2:17]
	ds_read_b64_tr_b16 v[86:87], v109 offset:11520
	ds_read_b64_tr_b16 v[88:89], v109 offset:12672
	v_cvt_pk_bf16_f32 v82, v90, v91
	v_cvt_pk_bf16_f32 v83, v92, v93
	v_cvt_pk_bf16_f32 v84, v94, v95
	v_cvt_pk_bf16_f32 v85, v96, v97
	v_cvt_pk_bf16_f32 v70, v123, v124
	v_cvt_pk_bf16_f32 v71, v125, v130
	s_waitcnt lgkmcnt(0)
	v_mfma_f32_32x32x16_bf16 v[18:33], v[86:89], v[82:85], v[18:33]
	ds_read_b64_tr_b16 v[86:87], v109 offset:11584
	ds_read_b64_tr_b16 v[88:89], v109 offset:12736
	v_cvt_pk_bf16_f32 v72, v131, v132
	v_cvt_pk_bf16_f32 v73, v150, v151
	v_exp_f32_e32 v155, v66
	v_cvt_pk_bf16_f32 v66, v111, v112
	v_cvt_pk_bf16_f32 v67, v113, v114
	v_cvt_pk_bf16_f32 v68, v152, v153
	s_waitcnt lgkmcnt(0)
	v_mfma_f32_32x32x16_bf16 v[2:17], v[86:89], v[82:85], v[2:17]
	ds_read_b64_tr_b16 v[86:87], v109 offset:13824
	ds_read_b64_tr_b16 v[88:89], v109 offset:14976
	v_cvt_pk_bf16_f32 v69, v154, v155
	v_mul_f32_e64 v64, v64, v0
	v_mul_f32_e64 v65, v65, v0
	v_pk_mul_f32 v[62:63], v[62:63], v[0:1] op_sel_hi:[1,0]
	v_pk_mul_f32 v[60:61], v[60:61], v[0:1] op_sel_hi:[1,0]
	v_pk_mul_f32 v[58:59], v[58:59], v[0:1] op_sel_hi:[1,0]
	v_pk_mul_f32 v[56:57], v[56:57], v[0:1] op_sel_hi:[1,0]
	s_waitcnt lgkmcnt(0)
	v_mfma_f32_32x32x16_bf16 v[18:33], v[86:89], v[70:73], v[18:33]
	ds_read_b64_tr_b16 v[86:87], v109 offset:13888
	ds_read_b64_tr_b16 v[88:89], v109 offset:15040
	v_mul_f32_e64 v54, v54, v0
	v_mul_f32_e64 v55, v55, v0
	v_mul_f32_e64 v52, v52, v0
	v_mul_f32_e64 v53, v53, v0
	v_pk_mul_f32 v[50:51], v[50:51], v[0:1] op_sel_hi:[1,0]
	v_pk_mul_f32 v[48:49], v[48:49], v[0:1] op_sel_hi:[1,0]
	v_pk_mul_f32 v[46:47], v[46:47], v[0:1] op_sel_hi:[1,0]
	v_pk_mul_f32 v[44:45], v[44:45], v[0:1] op_sel_hi:[1,0]
	s_waitcnt lgkmcnt(0)
	v_mfma_f32_32x32x16_bf16 v[2:17], v[86:89], v[70:73], v[2:17]
	ds_read_b64_tr_b16 v[86:87], v109 offset:16128
	ds_read_b64_tr_b16 v[88:89], v109 offset:17280
	v_mul_f32_e64 v42, v42, v0
	v_mul_f32_e64 v43, v43, v0
	v_mul_f32_e64 v40, v40, v0
	v_mul_f32_e64 v41, v41, v0
	v_pk_mul_f32 v[38:39], v[38:39], v[0:1] op_sel_hi:[1,0]
	v_pk_mul_f32 v[36:37], v[36:37], v[0:1] op_sel_hi:[1,0]
	v_pk_mul_f32 v[34:35], v[34:35], v[0:1] op_sel_hi:[1,0]
	v_fmac_f32_e32 v115, v101, v0
	s_waitcnt lgkmcnt(0)
	v_mfma_f32_32x32x16_bf16 v[18:33], v[86:89], v[66:69], v[18:33]
	ds_read_b64_tr_b16 v[86:87], v109 offset:16192
	ds_read_b64_tr_b16 v[88:89], v109 offset:17344
	v_add_f32_e32 v0, v116, v115
	v_add_f32_e32 v0, v117, v0
	v_add_f32_e32 v0, v118, v0
	v_add_f32_e32 v0, v119, v0
	v_add_f32_e32 v0, v120, v0
	v_add_f32_e32 v0, v121, v0
	s_waitcnt lgkmcnt(0)
	v_mfma_f32_32x32x16_bf16 v[2:17], v[86:89], v[66:69], v[2:17]
	v_cndmask_b32_e64 v86, v234, 0, s[0:1]
	v_cmp_ge_u32_e64 s[0:1], v110, v104
	s_or_b64 s[0:1], vcc, s[0:1]
	v_cmp_lt_i32_e32 vcc, v158, v103
	v_cndmask_b32_e64 v157, v234, 0, s[0:1]
	v_cmp_gt_u32_e64 s[0:1], v158, v104
	s_or_b64 s[0:1], vcc, s[0:1]
	v_cmp_lt_i32_e32 vcc, v159, v103
	v_cndmask_b32_e64 v87, v234, 0, s[0:1]
	v_cmp_gt_u32_e64 s[0:1], v110, v102
	s_or_b64 s[0:1], vcc, s[0:1]
	v_cmp_lt_i32_e32 vcc, v161, v103
	v_cndmask_b32_e64 v160, v234, 0, s[0:1]
	v_cmp_gt_u32_e64 s[0:1], v161, v104
	s_or_b64 s[0:1], vcc, s[0:1]
	v_cmp_lt_i32_e32 vcc, v162, v103
	v_cndmask_b32_e64 v88, v234, 0, s[0:1]
	v_cmp_gt_u32_e64 s[0:1], v162, v104
	s_or_b64 s[0:1], vcc, s[0:1]
	v_cmp_lt_i32_e32 vcc, v164, v103
	v_cndmask_b32_e64 v163, v234, 0, s[0:1]
	v_cmp_gt_u32_e64 s[0:1], v164, v104
	s_or_b64 s[0:1], vcc, s[0:1]
	v_cmp_lt_i32_e32 vcc, v165, v103
	v_cndmask_b32_e64 v89, v234, 0, s[0:1]
	v_cmp_gt_u32_e64 s[0:1], v165, v104
	s_or_b64 s[0:1], vcc, s[0:1]
	v_perm_b32 v88, v163, v88, s18
	v_cndmask_b32_e64 v176, v234, 0, s[0:1]
	v_perm_b32 v89, v176, v89, s18
	v_perm_b32 v87, v160, v87, s18
	v_perm_b32 v86, v157, v86, s18
	v_cmp_lt_u32_e32 vcc, v110, v105
	v_cmp_gt_u32_e64 s[0:1], v110, v106
	s_or_b64 s[0:1], vcc, s[0:1]
	v_mfma_f32_32x32x16_bf16 v[50:65], v[86:89], v[78:81], v[50:65]
	v_cndmask_b32_e64 v86, v234, 0, s[0:1]
	v_cmp_lt_u32_e32 vcc, v156, v105
	v_cmp_ge_u32_e64 s[0:1], v110, v106
	s_or_b64 s[0:1], vcc, s[0:1]
	v_cmp_lt_u32_e32 vcc, v158, v105
	v_cndmask_b32_e64 v156, v234, 0, s[0:1]
	v_cmp_gt_u32_e64 s[0:1], v158, v106
	s_or_b64 s[0:1], vcc, s[0:1]
	v_cmp_lt_u32_e32 vcc, v159, v105
	v_cndmask_b32_e64 v87, v234, 0, s[0:1]
	v_cmp_gt_u32_e64 s[0:1], v159, v106
	s_or_b64 s[0:1], vcc, s[0:1]
	v_cmp_lt_u32_e32 vcc, v161, v105
	v_cndmask_b32_e64 v157, v234, 0, s[0:1]
	v_cmp_gt_u32_e64 s[0:1], v161, v106
	s_or_b64 s[0:1], vcc, s[0:1]
	v_cmp_lt_u32_e32 vcc, v162, v105
	v_cndmask_b32_e64 v88, v234, 0, s[0:1]
	v_cmp_gt_u32_e64 s[0:1], v162, v106
	s_or_b64 s[0:1], vcc, s[0:1]
	v_cmp_lt_u32_e32 vcc, v164, v105
	v_cndmask_b32_e64 v158, v234, 0, s[0:1]
	v_cmp_gt_u32_e64 s[0:1], v164, v106
	s_or_b64 s[0:1], vcc, s[0:1]
	v_cmp_lt_u32_e32 vcc, v165, v105
	v_cndmask_b32_e64 v89, v234, 0, s[0:1]
	v_cmp_gt_u32_e64 s[0:1], v165, v106
	s_or_b64 s[0:1], vcc, s[0:1]
	v_perm_b32 v88, v158, v88, s18
	v_cndmask_b32_e64 v159, v234, 0, s[0:1]
	v_perm_b32 v89, v159, v89, s18
	v_perm_b32 v87, v157, v87, s18
	v_perm_b32 v86, v156, v86, s18
	v_add_u32_e32 v156, 19, v110
	v_add_u32_e32 v158, 24, v110
	v_mfma_f32_32x32x16_bf16 v[34:49], v[86:89], v[78:81], v[34:49]
	v_add_u32_e32 v86, 16, v110
	v_cmp_lt_i32_e32 vcc, v86, v103
	v_cmp_gt_u32_e64 s[0:1], v86, v104
	s_or_b64 s[0:1], vcc, s[0:1]
	v_add_u32_e32 v87, 17, v110
	v_cndmask_b32_e64 v78, v234, 0, s[0:1]
	v_cmp_lt_i32_e32 vcc, v87, v103
	v_cmp_gt_u32_e64 s[0:1], v87, v104
	s_or_b64 s[0:1], vcc, s[0:1]
	v_add_u32_e32 v89, 18, v110
	v_cndmask_b32_e64 v88, v234, 0, s[0:1]
; DI f32x16 mfma32(bf16x8 a, bf16x8 b, f32x16 c) { return __builtin_amdgcn_mfma_f32_32x32x16_bf16(a, b, c, 0, 0, 0); }
; DI void nsa_item(const Params& P0_, int b, int item, uchar* smem) {
;     ...
;       for (int sp = 0; sp < 4; ++sp) {
; #pragma unroll
;         for (int u = 0; u < 2; ++u) {
;           const int j = 32 * u + r31;
;           bf16x8 of;
; #pragma unroll
;           for (int jj = 0; jj < 8; ++jj) {
;             int n = n0 + 16 * sp + 8 * (jj >> 2) + 4 * h + (jj & 3);
;             of[jj] = (n >= 4 * j - 1 && n <= 4 * j + 3) ? (short)0x3F80 : (short)0;
;           }
;           O[2 + u] = mfma32(of, pf[sp], O[2 + u]);
;         }
;       }
	v_cmp_lt_i32_e32 vcc, v89, v103
	v_cmp_gt_u32_e64 s[0:1], v89, v104
	s_or_b64 s[0:1], vcc, s[0:1]
	v_cmp_lt_i32_e32 vcc, v156, v103
	v_cndmask_b32_e64 v79, v234, 0, s[0:1]
	v_cmp_gt_u32_e64 s[0:1], v156, v104
	s_or_b64 s[0:1], vcc, s[0:1]
	v_cmp_lt_i32_e32 vcc, v158, v103
	v_cndmask_b32_e64 v157, v234, 0, s[0:1]
	v_cmp_gt_u32_e64 s[0:1], v158, v104
	s_or_b64 s[0:1], vcc, s[0:1]
	v_add_u32_e32 v159, 25, v110
	v_cndmask_b32_e64 v80, v234, 0, s[0:1]
	v_cmp_lt_i32_e32 vcc, v159, v103
	v_cmp_gt_u32_e64 s[0:1], v159, v104
	s_or_b64 s[0:1], vcc, s[0:1]
	v_add_u32_e32 v161, 26, v110
	v_cndmask_b32_e64 v160, v234, 0, s[0:1]
	v_cmp_lt_i32_e32 vcc, v161, v103
	v_cmp_gt_u32_e64 s[0:1], v161, v104
	s_or_b64 s[0:1], vcc, s[0:1]
	v_add_u32_e32 v162, 27, v110
	v_cndmask_b32_e64 v81, v234, 0, s[0:1]
	v_cmp_lt_i32_e32 vcc, v162, v103
	v_cmp_gt_u32_e64 s[0:1], v162, v104
	s_or_b64 s[0:1], vcc, s[0:1]
	v_perm_b32 v80, v160, v80, s18
	v_cndmask_b32_e64 v163, v234, 0, s[0:1]
	v_perm_b32 v81, v163, v81, s18
	v_perm_b32 v79, v157, v79, s18
	v_perm_b32 v78, v88, v78, s18
	v_cmp_lt_u32_e32 vcc, v86, v105
	v_cmp_gt_u32_e64 s[0:1], v86, v106
	s_or_b64 s[0:1], vcc, s[0:1]
	v_mfma_f32_32x32x16_bf16 v[50:65], v[78:81], v[82:85], v[50:65]
	v_cndmask_b32_e64 v78, v234, 0, s[0:1]
	v_cmp_lt_u32_e32 vcc, v87, v105
	v_cmp_gt_u32_e64 s[0:1], v87, v106
	s_or_b64 s[0:1], vcc, s[0:1]
	v_cmp_lt_u32_e32 vcc, v89, v105
	v_cndmask_b32_e64 v86, v234, 0, s[0:1]
	v_cmp_gt_u32_e64 s[0:1], v89, v106
	s_or_b64 s[0:1], vcc, s[0:1]
	v_cmp_lt_u32_e32 vcc, v156, v105
	v_cndmask_b32_e64 v79, v234, 0, s[0:1]
	v_cmp_gt_u32_e64 s[0:1], v156, v106
	s_or_b64 s[0:1], vcc, s[0:1]
	v_cmp_lt_u32_e32 vcc, v158, v105
	v_cndmask_b32_e64 v87, v234, 0, s[0:1]
	v_cmp_gt_u32_e64 s[0:1], v158, v106
	s_or_b64 s[0:1], vcc, s[0:1]
	v_cmp_lt_u32_e32 vcc, v159, v105
	v_cndmask_b32_e64 v80, v234, 0, s[0:1]
	v_cmp_gt_u32_e64 s[0:1], v159, v106
	s_or_b64 s[0:1], vcc, s[0:1]
	v_cmp_lt_u32_e32 vcc, v161, v105
	v_cndmask_b32_e64 v88, v234, 0, s[0:1]
	v_cmp_gt_u32_e64 s[0:1], v161, v106
	s_or_b64 s[0:1], vcc, s[0:1]
	v_cmp_lt_u32_e32 vcc, v162, v105
	v_cndmask_b32_e64 v81, v234, 0, s[0:1]
	v_cmp_gt_u32_e64 s[0:1], v162, v106
	s_or_b64 s[0:1], vcc, s[0:1]
	v_perm_b32 v80, v88, v80, s18
	v_cndmask_b32_e64 v89, v234, 0, s[0:1]
	v_perm_b32 v81, v89, v81, s18
	v_perm_b32 v79, v87, v79, s18
	v_perm_b32 v78, v86, v78, s18
	v_add_u32_e32 v86, 35, v110
	v_add_u32_e32 v88, 40, v110
	v_mfma_f32_32x32x16_bf16 v[34:49], v[78:81], v[82:85], v[34:49]
	v_add_u32_e32 v82, 32, v110
	v_cmp_lt_i32_e32 vcc, v82, v103
	v_cmp_gt_u32_e64 s[0:1], v82, v104
	s_or_b64 s[0:1], vcc, s[0:1]
	v_add_u32_e32 v83, 33, v110
	v_cndmask_b32_e64 v78, v234, 0, s[0:1]
	v_cmp_lt_i32_e32 vcc, v83, v103
	v_cmp_gt_u32_e64 s[0:1], v83, v104
	s_or_b64 s[0:1], vcc, s[0:1]
	v_add_u32_e32 v85, 34, v110
	v_cndmask_b32_e64 v84, v234, 0, s[0:1]
	v_cmp_lt_i32_e32 vcc, v85, v103
	v_cmp_gt_u32_e64 s[0:1], v85, v104
	s_or_b64 s[0:1], vcc, s[0:1]
	v_cmp_lt_i32_e32 vcc, v86, v103
	v_cndmask_b32_e64 v79, v234, 0, s[0:1]
	v_cmp_gt_u32_e64 s[0:1], v86, v104
	s_or_b64 s[0:1], vcc, s[0:1]
	v_cmp_lt_i32_e32 vcc, v88, v103
	v_cndmask_b32_e64 v87, v234, 0, s[0:1]
	v_cmp_gt_u32_e64 s[0:1], v88, v104
	s_or_b64 s[0:1], vcc, s[0:1]
	v_add_u32_e32 v89, 41, v110
	v_cndmask_b32_e64 v80, v234, 0, s[0:1]
	v_cmp_lt_i32_e32 vcc, v89, v103
	v_cmp_gt_u32_e64 s[0:1], v89, v104
	s_or_b64 s[0:1], vcc, s[0:1]
	v_add_u32_e32 v157, 42, v110
	v_cndmask_b32_e64 v156, v234, 0, s[0:1]
	v_cmp_lt_i32_e32 vcc, v157, v103
	v_cmp_gt_u32_e64 s[0:1], v157, v104
	s_or_b64 s[0:1], vcc, s[0:1]
	v_add_u32_e32 v158, 43, v110
	v_cndmask_b32_e64 v81, v234, 0, s[0:1]
	v_cmp_lt_i32_e32 vcc, v158, v103
	v_cmp_gt_u32_e64 s[0:1], v158, v104
	s_or_b64 s[0:1], vcc, s[0:1]
	v_perm_b32 v80, v156, v80, s18
	v_cndmask_b32_e64 v159, v234, 0, s[0:1]
	v_perm_b32 v81, v159, v81, s18
	v_perm_b32 v79, v87, v79, s18
	v_perm_b32 v78, v84, v78, s18
	v_cmp_lt_u32_e32 vcc, v82, v105
	v_cmp_gt_u32_e64 s[0:1], v82, v106
	s_or_b64 s[0:1], vcc, s[0:1]
	v_mfma_f32_32x32x16_bf16 v[50:65], v[78:81], v[70:73], v[50:65]
	v_cndmask_b32_e64 v78, v234, 0, s[0:1]
	v_cmp_lt_u32_e32 vcc, v83, v105
	v_cmp_gt_u32_e64 s[0:1], v83, v106
	s_or_b64 s[0:1], vcc, s[0:1]
	v_cmp_lt_u32_e32 vcc, v85, v105
	v_cndmask_b32_e64 v82, v234, 0, s[0:1]
	v_cmp_gt_u32_e64 s[0:1], v85, v106
	s_or_b64 s[0:1], vcc, s[0:1]
	v_cmp_lt_u32_e32 vcc, v86, v105
	v_cndmask_b32_e64 v79, v234, 0, s[0:1]
	v_cmp_gt_u32_e64 s[0:1], v86, v106
; DI f32x16 mfma32(bf16x8 a, bf16x8 b, f32x16 c) { return __builtin_amdgcn_mfma_f32_32x32x16_bf16(a, b, c, 0, 0, 0); }
; template <int NO, bool COND = true>
; DI void softmax_step(f32x16 st[2], float& m, float& lsum, f32x16* O, bf16x8 pf[4]) {
;   float mx = fmaxf(m, fmaxf(max16(st[0]), max16(st[1])));
;   mx = fmaxf(mx, __shfl_xor(mx, 32, 64));
;   sm_rescale<NO, COND>(m, mx, lsum, O);
; #pragma unroll
;   for (int kt = 0; kt < 2; ++kt)
; #pragma unroll
;     for (int i = 0; i < 16; ++i) { float p = __builtin_amdgcn_exp2f(st[kt][i] - mx); lsum += p; st[kt][i] = p; }
; #pragma unroll
;   for (int kt = 0; kt < 2; ++kt) { pf[2 * kt] = pack8(st[kt], 0); pf[2 * kt + 1] = pack8(st[kt], 1); }
; }
; DI void nsa_item(const Params& P0_, int b, int item, uchar* smem) {
;     ...
;       for (int sp = 0; sp < 4; ++sp) {
; #pragma unroll
;         for (int u = 0; u < 2; ++u) {
;           const int j = 32 * u + r31;
;           bf16x8 of;
; #pragma unroll
;           for (int jj = 0; jj < 8; ++jj) {
;             int n = n0 + 16 * sp + 8 * (jj >> 2) + 4 * h + (jj & 3);
;             of[jj] = (n >= 4 * j - 1 && n <= 4 * j + 3) ? (short)0x3F80 : (short)0;
;           }
;           O[2 + u] = mfma32(of, pf[sp], O[2 + u]);
;         }
;       }
;     }
	s_or_b64 s[0:1], vcc, s[0:1]
	v_cmp_lt_u32_e32 vcc, v88, v105
	v_cndmask_b32_e64 v83, v234, 0, s[0:1]
	v_cmp_gt_u32_e64 s[0:1], v88, v106
	s_or_b64 s[0:1], vcc, s[0:1]
	v_cmp_lt_u32_e32 vcc, v89, v105
	v_cndmask_b32_e64 v80, v234, 0, s[0:1]
	v_cmp_gt_u32_e64 s[0:1], v89, v106
	s_or_b64 s[0:1], vcc, s[0:1]
	v_cmp_lt_u32_e32 vcc, v157, v105
	v_cndmask_b32_e64 v84, v234, 0, s[0:1]
	v_cmp_gt_u32_e64 s[0:1], v157, v106
	s_or_b64 s[0:1], vcc, s[0:1]
	v_cmp_lt_u32_e32 vcc, v158, v105
	v_cndmask_b32_e64 v81, v234, 0, s[0:1]
	v_cmp_gt_u32_e64 s[0:1], v158, v106
	s_or_b64 s[0:1], vcc, s[0:1]
	v_perm_b32 v80, v84, v80, s18
	v_cndmask_b32_e64 v85, v234, 0, s[0:1]
	v_perm_b32 v81, v85, v81, s18
	v_perm_b32 v79, v83, v79, s18
	v_perm_b32 v78, v82, v78, s18
	v_add_u32_e32 v82, 51, v110
	v_add_u32_e32 v84, 56, v110
	v_mfma_f32_32x32x16_bf16 v[34:49], v[78:81], v[70:73], v[34:49]
	v_add_u32_e32 v78, 48, v110
	v_cmp_lt_i32_e32 vcc, v78, v103
	v_cmp_gt_u32_e64 s[0:1], v78, v104
	s_or_b64 s[0:1], vcc, s[0:1]
	v_add_u32_e32 v79, 49, v110
	v_cndmask_b32_e64 v70, v234, 0, s[0:1]
	v_cmp_lt_i32_e32 vcc, v79, v103
	v_cmp_gt_u32_e64 s[0:1], v79, v104
	s_or_b64 s[0:1], vcc, s[0:1]
	v_add_u32_e32 v81, 50, v110
	v_cndmask_b32_e64 v80, v234, 0, s[0:1]
	v_cmp_lt_i32_e32 vcc, v81, v103
	v_cmp_gt_u32_e64 s[0:1], v81, v104
	s_or_b64 s[0:1], vcc, s[0:1]
	v_cmp_lt_i32_e32 vcc, v82, v103
	v_cndmask_b32_e64 v71, v234, 0, s[0:1]
	v_cmp_gt_u32_e64 s[0:1], v82, v104
	s_or_b64 s[0:1], vcc, s[0:1]
	v_cmp_lt_i32_e32 vcc, v84, v103
	v_cndmask_b32_e64 v83, v234, 0, s[0:1]
	v_cmp_gt_u32_e64 s[0:1], v84, v104
	s_or_b64 s[0:1], vcc, s[0:1]
	v_add_u32_e32 v85, 57, v110
	v_cndmask_b32_e64 v72, v234, 0, s[0:1]
	v_cmp_lt_i32_e32 vcc, v85, v103
	v_cmp_gt_u32_e64 s[0:1], v85, v104
	s_or_b64 s[0:1], vcc, s[0:1]
	v_add_u32_e32 v87, 58, v110
	v_cndmask_b32_e64 v86, v234, 0, s[0:1]
	v_cmp_lt_i32_e32 vcc, v87, v103
	v_cmp_gt_u32_e64 s[0:1], v87, v104
	s_or_b64 s[0:1], vcc, s[0:1]
	v_add_u32_e32 v88, 59, v110
	v_cndmask_b32_e64 v73, v234, 0, s[0:1]
	v_cmp_lt_i32_e32 vcc, v88, v103
	v_cmp_gt_u32_e64 s[0:1], v88, v104
	s_or_b64 s[0:1], vcc, s[0:1]
	v_perm_b32 v72, v86, v72, s18
	v_cndmask_b32_e64 v89, v234, 0, s[0:1]
	v_perm_b32 v73, v89, v73, s18
	v_perm_b32 v71, v83, v71, s18
	v_perm_b32 v70, v80, v70, s18
	v_cmp_lt_u32_e32 vcc, v78, v105
	v_cmp_gt_u32_e64 s[0:1], v78, v106
	s_or_b64 s[0:1], vcc, s[0:1]
	v_mfma_f32_32x32x16_bf16 v[50:65], v[70:73], v[66:69], v[50:65]
	v_cndmask_b32_e64 v70, v234, 0, s[0:1]
	v_cmp_lt_u32_e32 vcc, v79, v105
	v_cmp_gt_u32_e64 s[0:1], v79, v106
	s_or_b64 s[0:1], vcc, s[0:1]
	v_cmp_lt_u32_e32 vcc, v81, v105
	v_cndmask_b32_e64 v78, v234, 0, s[0:1]
	v_cmp_gt_u32_e64 s[0:1], v81, v106
	s_or_b64 s[0:1], vcc, s[0:1]
	v_add_f32_e32 v0, v122, v0
	v_cndmask_b32_e64 v71, v234, 0, s[0:1]
	v_cmp_lt_u32_e32 vcc, v82, v105
	v_cmp_gt_u32_e64 s[0:1], v82, v106
	v_add_f32_e32 v0, v90, v0
	s_or_b64 s[0:1], vcc, s[0:1]
	v_add_f32_e32 v0, v91, v0
	v_cndmask_b32_e64 v79, v234, 0, s[0:1]
	v_cmp_lt_u32_e32 vcc, v84, v105
	v_cmp_gt_u32_e64 s[0:1], v84, v106
	v_add_f32_e32 v0, v92, v0
	s_or_b64 s[0:1], vcc, s[0:1]
	v_add_f32_e32 v0, v93, v0
	v_cndmask_b32_e64 v72, v234, 0, s[0:1]
	v_cmp_lt_u32_e32 vcc, v85, v105
	v_cmp_gt_u32_e64 s[0:1], v85, v106
	v_add_f32_e32 v0, v94, v0
	s_or_b64 s[0:1], vcc, s[0:1]
	v_add_f32_e32 v0, v95, v0
	v_cndmask_b32_e64 v80, v234, 0, s[0:1]
	v_cmp_lt_u32_e32 vcc, v87, v105
	v_cmp_gt_u32_e64 s[0:1], v87, v106
	v_add_f32_e32 v0, v96, v0
	s_or_b64 s[0:1], vcc, s[0:1]
	v_add_f32_e32 v0, v97, v0
	v_cndmask_b32_e64 v73, v234, 0, s[0:1]
	v_cmp_lt_u32_e32 vcc, v88, v105
	v_cmp_gt_u32_e64 s[0:1], v88, v106
	v_add_f32_e32 v0, v123, v0
	s_or_b64 s[0:1], vcc, s[0:1]
	v_add_f32_e32 v0, v124, v0
	v_cndmask_b32_e64 v81, v234, 0, s[0:1]
	v_add_f32_e32 v0, v125, v0
	v_perm_b32 v73, v81, v73, s18
	v_perm_b32 v72, v80, v72, s18
	v_perm_b32 v71, v79, v71, s18
	v_perm_b32 v70, v78, v70, s18
	v_add_f32_e32 v0, v130, v0
	v_add_f32_e32 v0, v131, v0
	v_add_f32_e32 v0, v132, v0
	v_add_f32_e32 v0, v150, v0
	v_add_f32_e32 v0, v151, v0
	v_mfma_f32_32x32x16_bf16 v[34:49], v[70:73], v[66:69], v[34:49]
	v_add_f32_e32 v0, v111, v0
	v_add_f32_e32 v0, v112, v0
	v_add_f32_e32 v0, v113, v0
	v_add_f32_e32 v0, v114, v0
	v_add_f32_e32 v0, v152, v0
	v_add_f32_e32 v0, v153, v0
	s_add_u32 s6, s6, 0x2000
	v_add_f32_e32 v0, v154, v0
	s_addc_u32 s7, s7, 0
	v_add_f32_e32 v101, v155, v0
	s_cmp_eq_u32 s8, s9
	v_mov_b32_e32 v0, v77
	s_cbranch_scc0 .LBB0_616
